# prep1: second-round xg tasks reassigned from the bias/G half-workgroups to xg-only half-workgroups (grid 256 only, generic fallback)
# baseline (speedup 1.0000x reference)
.LBB0_87:
	s_cmpk_lg_i32 s70, 0x200
	s_cbranch_scc1 .Lp1_generic
	s_cmpk_gt_i32 s33, 0x1ff
	s_cbranch_scc1 .LBB0_105
	s_cmpk_lt_i32 s33, 0xa8
	s_cbranch_scc1 .LBB0_105
	s_cmpk_gt_i32 s33, 0x14f
	s_cbranch_scc1 .LBB0_105
	s_addk_i32 s33, 0x158
	v_add_u32_e32 v144, 0x1580, v144
	s_branch .LBB0_88
